# v28 (P1 gate prefetch, s[0:1] temporaries) + short scan tickets ordered mLSTM units first, SSD units last (longest-first)
# baseline (speedup 1.0000x reference)
.LBB0_218:
	s_add_i32 s0, s20, 0xfffff000
	s_lshr_b32 s1, s0, 11
	s_mulk_i32 s1, 0x3000
	s_add_i32 s4, s1, 0x3000
	s_cmpk_lt_i32 s20, 0x1000
	s_cselect_b32 s1, s21, 0
	s_cselect_b32 s0, s20, s0
	s_cselect_b32 s33, s37, s39
	s_cselect_b32 s62, s36, s38
	s_cselect_b32 s4, 0, s4
	s_lshl_b64 s[0:1], s[0:1], 13
	s_add_u32 s0, s62, s0
	s_addc_u32 s1, s33, s1
	s_lshl_b64 s[62:63], s[4:5], 2
	s_add_u32 s62, s10, s62
	s_addc_u32 s63, s11, s63
	s_add_u32 s68, s62, 0x2000
	v_lshl_add_u64 v[24:25], s[0:1], 0, v[110:111]
	s_addc_u32 s69, s63, 0
	global_load_dwordx4 v[44:47], v110, s[0:1]
	global_load_dwordx4 v[52:55], v110, s[0:1] offset:1024
	global_load_dwordx4 v[20:23], v[116:117], off
	global_load_dwordx4 v[16:19], v[116:117], off offset:1024
	global_load_dwordx4 v[162:165], v129, s[68:69]
	global_load_dwordx4 v[170:173], v183, s[68:69]
	global_load_dwordx4 v[4:7], v129, s[62:63]
	global_load_dwordx4 v[0:3], v129, s[62:63] offset:1024
	global_load_dwordx4 v[56:59], v110, s[0:1] offset:2048
	global_load_dwordx4 v[64:67], v110, s[0:1] offset:3072
	global_load_dwordx4 v[36:39], v[116:117], off offset:2048
	global_load_dwordx4 v[32:35], v[116:117], off offset:3072
	global_load_dwordx4 v[174:177], v186, s[68:69]
	global_load_dwordx4 v[198:201], v187, s[68:69]
	global_load_dwordx4 v[12:15], v129, s[62:63] offset:2048
	global_load_dwordx4 v[8:11], v129, s[62:63] offset:3072
	s_movk_i32 s0, 0x1000
	v_add_co_u32_e64 v48, s[0:1], s0, v24
	s_nop 1
	v_addc_co_u32_e64 v49, s[0:1], 0, v25, s[0:1]
	global_load_dwordx4 v[202:205], v188, s[68:69]
	global_load_dwordx4 v[24:27], v188, s[62:63]
	global_load_dwordx4 v[84:87], v[48:49], off
	global_load_dwordx4 v[80:83], v[48:49], off offset:1024
	global_load_dwordx4 v[68:71], v[118:119], off
	global_load_dwordx4 v[60:63], v[120:121], off
	global_load_dwordx4 v[104:107], v189, s[68:69]
	global_load_dwordx4 v[28:31], v189, s[62:63]
	global_load_dwordx4 v[100:103], v190, s[68:69]
	global_load_dwordx4 v[40:43], v190, s[62:63]
	global_load_dwordx4 v[92:95], v[48:49], off offset:2048
	global_load_dwordx4 v[88:91], v[48:49], off offset:3072
	global_load_dwordx4 v[76:79], v[122:123], off
	global_load_dwordx4 v[72:75], v[124:125], off
	global_load_dwordx4 v[96:99], v191, s[68:69]
	s_nop 0
	global_load_dwordx4 v[48:51], v191, s[62:63]
	s_waitcnt vmcnt(31)
	v_mov_b32_e32 v142, v45
	s_waitcnt vmcnt(30)
	v_mov_b32_e32 v143, v53
	v_mov_b32_e32 v146, v47
	v_mov_b32_e32 v147, v55
	v_mov_b32_e32 v138, v44
	v_mov_b32_e32 v139, v52
	v_mov_b32_e32 v140, v46
	v_mov_b32_e32 v141, v54
	s_waitcnt vmcnt(23)
	v_pk_mul_f32 v[148:149], v[58:59], v[58:59]
	v_pk_mul_f32 v[144:145], v[56:57], v[56:57]
	v_pk_mul_f32 v[142:143], v[142:143], v[142:143]
	v_pk_mul_f32 v[146:147], v[146:147], v[146:147]
	v_pk_add_f32 v[152:153], v[162:163], 1.0 op_sel_hi:[1,0]
	v_pk_add_f32 v[162:163], v[172:173], 1.0 op_sel_hi:[1,0]
	s_waitcnt vmcnt(19)
	v_pk_add_f32 v[172:173], v[174:175], 1.0 op_sel_hi:[1,0]
	s_waitcnt vmcnt(18)
	v_pk_add_f32 v[174:175], v[200:201], 1.0 op_sel_hi:[1,0]
	s_waitcnt vmcnt(15)
	v_pk_add_f32 v[200:201], v[202:203], 1.0 op_sel_hi:[1,0]
	v_pk_mov_b32 v[202:203], v[144:145], v[148:149] op_sel:[1,0]
	v_mov_b32_e32 v145, v149
	v_pk_fma_f32 v[138:139], v[138:139], v[138:139], v[142:143]
	v_pk_fma_f32 v[140:141], v[140:141], v[140:141], v[146:147]
	v_mul_f32_e32 v156, v65, v65
	v_mul_f32_e32 v158, v67, v67
	v_pk_add_f32 v[142:143], v[202:203], v[144:145]
	v_pk_add_f32 v[138:139], v[138:139], v[140:141]
	s_waitcnt vmcnt(13)
	v_mul_f32_e32 v133, v84, v84
	v_mul_f32_e32 v210, v85, v85
	v_mul_f32_e32 v211, v86, v86
	v_mul_f32_e32 v212, v87, v87
	v_pk_add_f32 v[150:151], v[164:165], 1.0 op_sel_hi:[1,0]
	v_pk_add_f32 v[164:165], v[170:171], 1.0 op_sel_hi:[1,0]
	v_pk_add_f32 v[170:171], v[176:177], 1.0 op_sel_hi:[1,0]
	v_pk_add_f32 v[176:177], v[198:199], 1.0 op_sel_hi:[1,0]
	v_pk_add_f32 v[198:199], v[204:205], 1.0 op_sel_hi:[1,0]
	v_pk_fma_f32 v[148:149], v[64:65], v[64:65], v[156:157] op_sel_hi:[1,1,0]
	v_pk_fma_f32 v[204:205], v[66:67], v[66:67], v[158:159] op_sel_hi:[1,1,0]
	v_pk_add_f32 v[140:141], v[142:143], v[142:143] op_sel:[0,1] op_sel_hi:[1,0]
	v_pk_add_f32 v[138:139], v[138:139], v[138:139] op_sel:[0,1] op_sel_hi:[1,0]
	s_waitcnt vmcnt(12)
	v_pk_mul_f32 v[160:161], v[82:83], v[82:83]
	v_pk_mul_f32 v[154:155], v[80:81], v[80:81]
	v_mov_b32_e32 v149, v211
	v_mov_b32_e32 v205, v212
	v_mov_b32_e32 v141, v210
	v_mov_b32_e32 v139, v133
	v_pk_mov_b32 v[206:207], v[154:155], v[160:161] op_sel:[1,0]
	v_mov_b32_e32 v155, v161
	v_pk_add_f32 v[142:143], v[148:149], v[204:205]
	v_pk_add_f32 v[138:139], v[138:139], v[140:141]
	s_waitcnt vmcnt(5)
	v_mul_f32_e32 v166, v93, v93
	v_mul_f32_e32 v168, v95, v95
	v_pk_add_f32 v[144:145], v[206:207], v[154:155]
	v_pk_add_f32 v[138:139], v[138:139], v[142:143]
	s_waitcnt vmcnt(4)
	v_mul_f32_e32 v213, v88, v88
	v_mul_f32_e32 v214, v89, v89
	v_mul_f32_e32 v215, v90, v90
	v_mul_f32_e32 v216, v91, v91
	v_pk_fma_f32 v[160:161], v[92:93], v[92:93], v[166:167] op_sel_hi:[1,1,0]
	v_pk_fma_f32 v[208:209], v[94:95], v[94:95], v[168:169] op_sel_hi:[1,1,0]
	v_pk_add_f32 v[144:145], v[144:145], v[144:145] op_sel:[0,1] op_sel_hi:[1,0]
	v_pk_add_f32 v[138:139], v[138:139], v[138:139] op_sel:[0,1] op_sel_hi:[1,0]
	v_mov_b32_e32 v161, v215
	v_mov_b32_e32 v209, v216
	v_mov_b32_e32 v145, v214
	v_mov_b32_e32 v139, v213
	v_pk_add_f32 v[146:147], v[160:161], v[208:209]
	v_pk_add_f32 v[138:139], v[138:139], v[144:145]
	v_lshl_add_u64 v[178:179], s[28:29], 0, v[136:137]
	v_pk_add_f32 v[138:139], v[138:139], v[146:147]
	v_add_co_u32_e64 v178, s[0:1], s16, v178
	v_add_f32_e32 v133, v138, v139
	ds_bpermute_b32 v138, v109, v133
	v_lshl_add_u64 v[180:181], s[28:29], 0, v[134:135]
	v_addc_co_u32_e64 v179, s[0:1], 0, v179, s[0:1]
	v_add_co_u32_e64 v180, s[0:1], s17, v180
	s_waitcnt lgkmcnt(0)
	v_add_f32_e32 v133, v133, v138
	ds_bpermute_b32 v138, v113, v133
	s_mov_b32 s4, 0x800000
	v_addc_co_u32_e64 v181, s[0:1], 0, v181, s[0:1]
	v_mov_b32_e32 v218, v111
	s_waitcnt lgkmcnt(0)
	v_add_f32_e32 v133, v133, v138
	ds_bpermute_b32 v138, v115, v133
	v_mov_b32_e32 v219, v111
	v_pk_add_f32 v[106:107], v[106:107], 1.0 op_sel_hi:[1,0]
	v_pk_add_f32 v[104:105], v[104:105], 1.0 op_sel_hi:[1,0]
	v_pk_add_f32 v[100:101], v[100:101], 1.0 op_sel_hi:[1,0]
	s_waitcnt lgkmcnt(0)
	v_add_f32_e32 v133, v133, v138
	ds_bpermute_b32 v138, v157, v133
	s_waitcnt vmcnt(1)
	v_pk_add_f32 v[96:97], v[96:97], 1.0 op_sel_hi:[1,0]
	v_mov_b32_e32 v220, v111
	v_mov_b32_e32 v221, v111
	v_mov_b32_e32 v222, v111
	s_waitcnt lgkmcnt(0)
	v_add_f32_e32 v133, v133, v138
	ds_bpermute_b32 v138, v159, v133
	v_mov_b32_e32 v223, v111
	v_mov_b32_e32 v224, v111
	v_mov_b32_e32 v225, v111
	v_add_u32_e32 v217, s7, v169
	s_waitcnt lgkmcnt(0)
	v_add_f32_e32 v133, v133, v138
	ds_bpermute_b32 v138, v167, v133
	s_addk_i32 s7, 0x1010
	s_add_u32 s20, s20, 1
	v_pk_add_f32 v[102:103], v[102:103], 1.0 op_sel_hi:[1,0]
	v_pk_add_f32 v[98:99], v[98:99], 1.0 op_sel_hi:[1,0]
	s_waitcnt lgkmcnt(0)
	v_add_f32_e32 v133, v133, v138
	v_fmamk_f32 v133, v133, 0x3a000000, v192
	v_mul_f32_e32 v138, 0x4b800000, v133
	v_cmp_gt_f32_e64 s[0:1], s4, v133
	s_addc_u32 s21, s21, 0
	v_lshl_add_u64 v[134:135], v[134:135], 0, s[8:9]
	v_cndmask_b32_e64 v133, v133, v138, s[0:1]
	v_rsq_f32_e32 v133, v133
	v_lshl_add_u64 v[136:137], v[136:137], 0, s[12:13]
	s_cmpk_eq_i32 s7, 0x4040
	v_mul_f32_e32 v138, 0x45800000, v133
	v_cndmask_b32_e64 v138, v133, v138, s[0:1]
	v_pk_mul_f32 v[44:45], v[44:45], v[138:139] op_sel_hi:[1,0]
	v_pk_mul_f32 v[52:53], v[52:53], v[138:139] op_sel_hi:[1,0]
	v_pk_mul_f32 v[20:21], v[20:21], v[44:45]
	v_pk_mul_f32 v[16:17], v[16:17], v[52:53]
	v_pk_fma_f32 v[4:5], v[152:153], v[20:21], v[4:5]
	v_pk_mul_f32 v[46:47], v[46:47], v[138:139] op_sel_hi:[1,0]
	v_cvt_pk_fp8_f32 v218, v4, v5
	v_pk_mul_f32 v[54:55], v[54:55], v[138:139] op_sel_hi:[1,0]
	v_pk_mul_f32 v[56:57], v[56:57], v[138:139] op_sel_hi:[1,0]
	v_pk_mul_f32 v[64:65], v[64:65], v[138:139] op_sel_hi:[1,0]
	v_pk_mul_f32 v[86:87], v[86:87], v[138:139] op_sel_hi:[1,0]
	v_pk_mul_f32 v[84:85], v[84:85], v[138:139] op_sel_hi:[1,0]
	v_pk_mul_f32 v[82:83], v[82:83], v[138:139] op_sel_hi:[1,0]
	v_pk_mul_f32 v[80:81], v[80:81], v[138:139] op_sel_hi:[1,0]
	v_pk_mul_f32 v[92:93], v[92:93], v[138:139] op_sel_hi:[1,0]
	v_pk_mul_f32 v[88:89], v[88:89], v[138:139] op_sel_hi:[1,0]
	v_pk_fma_f32 v[0:1], v[164:165], v[16:17], v[0:1]
	v_pk_mul_f32 v[22:23], v[22:23], v[46:47]
	v_pk_mul_f32 v[18:19], v[18:19], v[54:55]
	v_pk_mul_f32 v[36:37], v[36:37], v[56:57]
	v_pk_mul_f32 v[32:33], v[32:33], v[64:65]
	v_pk_mul_f32 v[44:45], v[68:69], v[84:85]
	v_pk_mul_f32 v[46:47], v[70:71], v[86:87]
	v_pk_mul_f32 v[52:53], v[60:61], v[80:81]
	v_pk_mul_f32 v[54:55], v[62:63], v[82:83]
	v_pk_mul_f32 v[56:57], v[76:77], v[92:93]
	v_pk_mul_f32 v[60:61], v[72:73], v[88:89]
	v_cvt_pk_fp8_f32 v219, v0, v1
	v_pk_fma_f32 v[6:7], v[150:151], v[22:23], v[6:7]
	v_pk_fma_f32 v[2:3], v[162:163], v[18:19], v[2:3]
	v_pk_fma_f32 v[12:13], v[172:173], v[36:37], v[12:13]
	v_pk_fma_f32 v[8:9], v[176:177], v[32:33], v[8:9]
	v_pk_fma_f32 v[16:17], v[198:199], v[46:47], v[26:27]
	v_pk_fma_f32 v[18:19], v[200:201], v[44:45], v[24:25]
	v_pk_fma_f32 v[20:21], v[106:107], v[54:55], v[30:31]
	v_pk_fma_f32 v[22:23], v[104:105], v[52:53], v[28:29]
	v_pk_fma_f32 v[26:27], v[100:101], v[56:57], v[40:41]
	s_waitcnt vmcnt(0)
	v_pk_fma_f32 v[30:31], v[96:97], v[60:61], v[48:49]
	v_cvt_pk_fp8_f32 v220, v12, v13
	v_cvt_pk_fp8_f32 v221, v8, v9
	v_cvt_pk_fp8_f32 v222, v18, v19
	v_cvt_pk_fp8_f32 v223, v22, v23
	v_cvt_pk_fp8_f32 v224, v26, v27
	v_cvt_pk_fp8_f32 v225, v30, v31
	v_cvt_pk_fp8_f32 v218, v6, v7 op_sel:[0,0,1]
	v_pk_mul_f32 v[58:59], v[58:59], v[138:139] op_sel_hi:[1,0]
	v_pk_mul_f32 v[66:67], v[66:67], v[138:139] op_sel_hi:[1,0]
	v_pk_mul_f32 v[94:95], v[94:95], v[138:139] op_sel_hi:[1,0]
	v_pk_mul_f32 v[90:91], v[90:91], v[138:139] op_sel_hi:[1,0]
	v_pk_mul_f32 v[38:39], v[38:39], v[58:59]
	v_pk_mul_f32 v[34:35], v[34:35], v[66:67]
	v_pk_mul_f32 v[58:59], v[78:79], v[94:95]
	v_pk_mul_f32 v[62:63], v[74:75], v[90:91]
	v_cvt_pk_fp8_f32 v219, v2, v3 op_sel:[0,0,1]
	v_pk_fma_f32 v[14:15], v[170:171], v[38:39], v[14:15]
	v_pk_fma_f32 v[10:11], v[174:175], v[34:35], v[10:11]
	v_pk_fma_f32 v[24:25], v[102:103], v[58:59], v[42:43]
	v_pk_fma_f32 v[28:29], v[98:99], v[62:63], v[50:51]
	v_cvt_pk_bf16_f32 v32, v4, v5
	v_cvt_pk_bf16_f32 v33, v6, v7
	v_cvt_pk_bf16_f32 v4, v0, v1
	v_cvt_pk_bf16_f32 v5, v2, v3
	v_cvt_pk_bf16_f32 v0, v12, v13
	v_cvt_pk_bf16_f32 v1, v14, v15
	v_cvt_pk_bf16_f32 v12, v8, v9
	v_cvt_pk_bf16_f32 v13, v10, v11
	v_cvt_pk_bf16_f32 v8, v18, v19
	v_cvt_pk_bf16_f32 v9, v16, v17
	v_cvt_pk_bf16_f32 v18, v22, v23
	v_cvt_pk_bf16_f32 v19, v20, v21
	v_cvt_pk_bf16_f32 v22, v26, v27
	v_cvt_pk_bf16_f32 v23, v24, v25
	v_cvt_pk_bf16_f32 v26, v30, v31
	v_cvt_pk_bf16_f32 v27, v28, v29
	global_store_dwordx2 v[178:179], v[32:33], off sc1
	ds_write2st64_b64 v217, v[32:33], v[4:5] offset1:1
	ds_write2st64_b64 v217, v[0:1], v[12:13] offset0:2 offset1:3
	ds_write2st64_b64 v217, v[8:9], v[18:19] offset0:4 offset1:5
	ds_write2st64_b64 v217, v[22:23], v[26:27] offset0:6 offset1:7
	v_cvt_pk_fp8_f32 v220, v14, v15 op_sel:[0,0,1]
	v_cvt_pk_fp8_f32 v221, v10, v11 op_sel:[0,0,1]
	v_cvt_pk_fp8_f32 v222, v16, v17 op_sel:[0,0,1]
	v_cvt_pk_fp8_f32 v223, v20, v21 op_sel:[0,0,1]
	v_cvt_pk_fp8_f32 v224, v24, v25 op_sel:[0,0,1]
	v_cvt_pk_fp8_f32 v225, v28, v29 op_sel:[0,0,1]
	global_store_dword v[180:181], v218, off sc1
	global_store_dwordx2 v[178:179], v[4:5], off offset:512 sc1
	global_store_dword v[180:181], v219, off offset:256 sc1
	global_store_dwordx2 v[178:179], v[0:1], off offset:1024 sc1
	global_store_dword v[180:181], v220, off offset:512 sc1
	global_store_dwordx2 v[178:179], v[12:13], off offset:1536 sc1
	global_store_dword v[180:181], v221, off offset:768 sc1
	global_store_dwordx2 v[178:179], v[8:9], off offset:2048 sc1
	global_store_dword v[180:181], v222, off offset:1024 sc1
	global_store_dwordx2 v[178:179], v[18:19], off offset:2560 sc1
	global_store_dword v[180:181], v223, off offset:1280 sc1
	global_store_dwordx2 v[178:179], v[22:23], off offset:3072 sc1
	global_store_dword v[180:181], v224, off offset:1536 sc1
	global_store_dwordx2 v[178:179], v[26:27], off offset:3584 sc1
	global_store_dword v[180:181], v225, off offset:1792 sc1
	s_cbranch_scc0 .LBB0_218
	v_mov_b32_e32 v0, 0
	v_mov_b32_e32 v1, v0
	v_mov_b32_e32 v2, v0
	v_mov_b32_e32 v3, v0
	v_mov_b32_e32 v12, v0
	v_mov_b32_e32 v13, v0
	v_mov_b32_e32 v14, v0
	v_mov_b32_e32 v15, v0
	v_mov_b32_e32 v8, v0
	v_mov_b32_e32 v9, v0
	v_mov_b32_e32 v10, v0
	v_mov_b32_e32 v11, v0
	v_mov_b32_e32 v16, v0
	v_mov_b32_e32 v17, v0
	v_mov_b32_e32 v18, v0
	v_mov_b32_e32 v19, v0
	v_mov_b32_e32 v4, v0
	v_mov_b32_e32 v5, v0
	v_mov_b32_e32 v6, v0
	v_mov_b32_e32 v7, v0
	v_mov_b32_e32 v20, v0
	v_mov_b32_e32 v21, v0
	v_mov_b32_e32 v22, v0
	v_mov_b32_e32 v23, v0
	v_mov_b32_e32 v148, v128
	v_ashrrev_i32_e32 v149, 31, v128
	v_lshl_add_u64 v[148:149], v[148:149], 1, v[126:127]
	s_mov_b64 s[0:1], 0x10000
	v_add_u32_e32 v150, 0x10100, v182
	v_lshl_add_u64 v[164:165], v[148:149], 0, s[0:1]
	s_mov_b64 s[0:1], 0x20000
	v_lshl_add_u64 v[170:171], v[148:149], 0, s[0:1]
	global_load_dwordx4 v[28:31], v[148:149], off
	global_load_dwordx4 v[32:35], v[164:165], off
	global_load_dwordx4 v[36:39], v[170:171], off
	global_load_dwordx4 v[40:43], v[148:149], off offset:64
	global_load_dwordx4 v[44:47], v[164:165], off offset:64
	global_load_dwordx4 v[48:51], v[170:171], off offset:64
	global_load_dwordx4 v[136:139], v[148:149], off offset:128
	global_load_dwordx4 v[140:143], v[164:165], off offset:128
	global_load_dwordx4 v[144:147], v[170:171], off offset:128
	global_load_dwordx4 v[160:163], v[148:149], off offset:192
	global_load_dwordx4 v[198:201], v[164:165], off offset:192
	global_load_dwordx4 v[202:205], v[170:171], off offset:192
	global_load_dwordx4 v[206:209], v[148:149], off offset:256
	global_load_dwordx4 v[210:213], v[164:165], off offset:256
	global_load_dwordx4 v[214:217], v[170:171], off offset:256
	global_load_dwordx4 v[218:221], v[148:149], off offset:320
	global_load_dwordx4 v[222:225], v[164:165], off offset:320
	global_load_dwordx4 v[226:229], v[170:171], off offset:320
	global_load_dwordx4 v[230:233], v[148:149], off offset:384
	global_load_dwordx4 v[234:237], v[164:165], off offset:384
	global_load_dwordx4 v[238:241], v[170:171], off offset:384
	s_waitcnt lgkmcnt(0)
	s_barrier
	ds_read_b128 v[24:27], v182
	ds_read_b128 v[152:155], v150
	ds_read_b128 v[178:181], v182 offset:64
	ds_read_b128 v[246:249], v150 offset:64
	s_waitcnt vmcnt(18) lgkmcnt(2)
	v_mfma_f32_16x16x32_bf16 v[0:3], v[24:27], v[28:31], v[0:3]
	v_mfma_f32_16x16x32_bf16 v[16:19], v[152:155], v[28:31], v[16:19]
	v_mfma_f32_16x16x32_bf16 v[12:15], v[24:27], v[32:35], v[12:15]
	v_mfma_f32_16x16x32_bf16 v[4:7], v[152:155], v[32:35], v[4:7]
	v_mfma_f32_16x16x32_bf16 v[8:11], v[24:27], v[36:39], v[8:11]
	v_mfma_f32_16x16x32_bf16 v[20:23], v[152:155], v[36:39], v[20:23]
	global_load_dwordx4 v[28:31], v[148:149], off offset:448
	global_load_dwordx4 v[32:35], v[164:165], off offset:448
	global_load_dwordx4 v[36:39], v[170:171], off offset:448
	ds_read_b128 v[24:27], v182 offset:128
	ds_read_b128 v[152:155], v150 offset:128
	s_waitcnt vmcnt(18) lgkmcnt(2)
	v_mfma_f32_16x16x32_bf16 v[0:3], v[178:181], v[40:43], v[0:3]
	v_mfma_f32_16x16x32_bf16 v[16:19], v[246:249], v[40:43], v[16:19]
	v_mfma_f32_16x16x32_bf16 v[12:15], v[178:181], v[44:47], v[12:15]
	v_mfma_f32_16x16x32_bf16 v[4:7], v[246:249], v[44:47], v[4:7]
	v_mfma_f32_16x16x32_bf16 v[8:11], v[178:181], v[48:51], v[8:11]
	v_mfma_f32_16x16x32_bf16 v[20:23], v[246:249], v[48:51], v[20:23]
	ds_read_b128 v[178:181], v182 offset:192
	ds_read_b128 v[246:249], v150 offset:192
	s_waitcnt vmcnt(15) lgkmcnt(2)
	v_mfma_f32_16x16x32_bf16 v[0:3], v[24:27], v[136:139], v[0:3]
	v_mfma_f32_16x16x32_bf16 v[16:19], v[152:155], v[136:139], v[16:19]
	v_mfma_f32_16x16x32_bf16 v[12:15], v[24:27], v[140:143], v[12:15]
	v_mfma_f32_16x16x32_bf16 v[4:7], v[152:155], v[140:143], v[4:7]
	v_mfma_f32_16x16x32_bf16 v[8:11], v[24:27], v[144:147], v[8:11]
	v_mfma_f32_16x16x32_bf16 v[20:23], v[152:155], v[144:147], v[20:23]
	ds_read_b128 v[24:27], v182 offset:256
	ds_read_b128 v[152:155], v150 offset:256
	s_waitcnt vmcnt(12) lgkmcnt(2)
	v_mfma_f32_16x16x32_bf16 v[0:3], v[178:181], v[160:163], v[0:3]
	v_mfma_f32_16x16x32_bf16 v[16:19], v[246:249], v[160:163], v[16:19]
	v_mfma_f32_16x16x32_bf16 v[12:15], v[178:181], v[198:201], v[12:15]
	v_mfma_f32_16x16x32_bf16 v[4:7], v[246:249], v[198:201], v[4:7]
	v_mfma_f32_16x16x32_bf16 v[8:11], v[178:181], v[202:205], v[8:11]
	v_mfma_f32_16x16x32_bf16 v[20:23], v[246:249], v[202:205], v[20:23]
	ds_read_b128 v[178:181], v182 offset:320
	ds_read_b128 v[246:249], v150 offset:320
	s_waitcnt vmcnt(9) lgkmcnt(2)
	v_mfma_f32_16x16x32_bf16 v[0:3], v[24:27], v[206:209], v[0:3]
	v_mfma_f32_16x16x32_bf16 v[16:19], v[152:155], v[206:209], v[16:19]
	v_mfma_f32_16x16x32_bf16 v[12:15], v[24:27], v[210:213], v[12:15]
	v_mfma_f32_16x16x32_bf16 v[4:7], v[152:155], v[210:213], v[4:7]
	v_mfma_f32_16x16x32_bf16 v[8:11], v[24:27], v[214:217], v[8:11]
	v_mfma_f32_16x16x32_bf16 v[20:23], v[152:155], v[214:217], v[20:23]
	ds_read_b128 v[24:27], v182 offset:384
	ds_read_b128 v[152:155], v150 offset:384
	s_waitcnt vmcnt(6) lgkmcnt(2)
	v_mfma_f32_16x16x32_bf16 v[0:3], v[178:181], v[218:221], v[0:3]
	v_mfma_f32_16x16x32_bf16 v[16:19], v[246:249], v[218:221], v[16:19]
	v_mfma_f32_16x16x32_bf16 v[12:15], v[178:181], v[222:225], v[12:15]
	v_mfma_f32_16x16x32_bf16 v[4:7], v[246:249], v[222:225], v[4:7]
	v_mfma_f32_16x16x32_bf16 v[8:11], v[178:181], v[226:229], v[8:11]
	v_mfma_f32_16x16x32_bf16 v[20:23], v[246:249], v[226:229], v[20:23]
	ds_read_b128 v[178:181], v182 offset:448
	ds_read_b128 v[246:249], v150 offset:448
	s_waitcnt vmcnt(3) lgkmcnt(2)
	v_mfma_f32_16x16x32_bf16 v[0:3], v[24:27], v[230:233], v[0:3]
	v_mfma_f32_16x16x32_bf16 v[16:19], v[152:155], v[230:233], v[16:19]
	v_mfma_f32_16x16x32_bf16 v[12:15], v[24:27], v[234:237], v[12:15]
	v_mfma_f32_16x16x32_bf16 v[4:7], v[152:155], v[234:237], v[4:7]
	v_mfma_f32_16x16x32_bf16 v[8:11], v[24:27], v[238:241], v[8:11]
	v_mfma_f32_16x16x32_bf16 v[20:23], v[152:155], v[238:241], v[20:23]
	s_waitcnt vmcnt(0) lgkmcnt(0)
	v_mfma_f32_16x16x32_bf16 v[0:3], v[178:181], v[28:31], v[0:3]
	v_mfma_f32_16x16x32_bf16 v[16:19], v[246:249], v[28:31], v[16:19]
	v_mfma_f32_16x16x32_bf16 v[12:15], v[178:181], v[32:35], v[12:15]
	v_mfma_f32_16x16x32_bf16 v[4:7], v[246:249], v[32:35], v[4:7]
	v_mfma_f32_16x16x32_bf16 v[8:11], v[178:181], v[36:39], v[8:11]
	v_mfma_f32_16x16x32_bf16 v[20:23], v[246:249], v[36:39], v[20:23]
	s_barrier
	ds_write_b32 v193, v0
	ds_write_b32 v193, v1 offset:192
	ds_write_b32 v193, v2 offset:384
	ds_write_b32 v194, v3
	ds_write_b32 v193, v12 offset:64
	ds_write_b32 v193, v13 offset:256
	ds_write_b32 v193, v14 offset:448
	ds_write_b32 v194, v15 offset:64
	ds_write_b32 v193, v8 offset:128
	ds_write_b32 v193, v9 offset:320
	ds_write_b32 v193, v10 offset:512
	ds_write_b32 v194, v11 offset:128
	ds_write_b32 v193, v16 offset:3072
	ds_write_b32 v193, v17 offset:3264
	ds_write_b32 v193, v18 offset:3456
	ds_write_b32 v195, v19
	ds_write_b32 v193, v4 offset:3136
	ds_write_b32 v193, v5 offset:3328
	ds_write_b32 v193, v6 offset:3520
	ds_write_b32 v195, v7 offset:64
	ds_write_b32 v193, v20 offset:3200
	ds_write_b32 v193, v21 offset:3392
	ds_write_b32 v193, v22 offset:3584
	ds_write_b32 v195, v23 offset:128
	s_waitcnt lgkmcnt(0)
	s_barrier
	s_and_saveexec_b64 s[20:21], vcc
	s_cbranch_execz .LBB0_216
	s_lshl_b32 s4, s85, 5
	v_lshl_add_u32 v1, v108, 2, 0
	s_mov_b64 s[62:63], 0
	v_mov_b32_e32 v0, v108
	s_branch .LBB0_224

.LBB0_586:
	s_or_b64 exec, exec, s[46:47]
	v_mov_b32_e32 v0, s35
	s_waitcnt lgkmcnt(0)
	s_barrier
	ds_read_b32 v0, v0
	s_movk_i32 s20, 0x3ff
	s_mov_b32 s16, 2
	s_waitcnt lgkmcnt(0)
	v_cmp_lt_i32_e32 vcc, s20, v0
	s_movk_i32 s20, 0x400
	v_readfirstlane_b32 s17, v0
	v_cmp_gt_i32_e64 s[46:47], s20, v0
	s_cbranch_vccnz .LBB0_588
	s_cmp_lt_u32 s17, 0x200
	s_cselect_b64 s[12:13], -1, 0
	s_and_b32 s66, s17, 0x1ff
	s_mov_b32 s16, 0
	s_mov_b64 s[14:15], 0
